# GEMM store epilogues: removed the compiler's acc+0.0 packed adds (zero bias) and the register shuffles they implied; wide-store WAR padding re-derived
# speedup vs baseline: 1.0072x; 1.0049x over previous
.LBB0_282:
	v_lshl_add_u32 v152, s38, 8, v146
	v_lshl_or_b32 v144, s16, 8, v148
	v_ashrrev_i32_e32 v153, 31, v152
	v_ashrrev_i32_e32 v145, 31, v144
	v_lshlrev_b64 v[154:155], 12, v[152:153]
	v_lshl_add_u64 v[154:155], s[58:59], 0, v[154:155]
	v_lshlrev_b64 v[156:157], 1, v[144:145]
	v_lshl_add_u64 v[144:145], v[154:155], 0, v[156:157]
	v_cvt_pk_bf16_f32 v123, v122, v123
	v_cvt_pk_bf16_f32 v122, v120, v121
	v_cvt_pk_bf16_f32 v120, v124, v125
	v_cvt_pk_bf16_f32 v121, v126, v127
	global_store_dwordx4 v[144:145], v[120:123], off
	v_cvt_pk_bf16_f32 v107, v106, v107
	v_cvt_pk_bf16_f32 v106, v104, v105
	v_cvt_pk_bf16_f32 v104, v112, v113
	v_cvt_pk_bf16_f32 v105, v114, v115
	global_store_dwordx4 v[144:145], v[104:107], off offset:256
	s_nop 1
	v_or_b32_e32 v104, 16, v152
	v_ashrrev_i32_e32 v105, 31, v104
	v_lshlrev_b64 v[104:105], 12, v[104:105]
	v_lshl_add_u64 v[104:105], s[58:59], 0, v[104:105]
	v_lshl_add_u64 v[112:113], v[104:105], 0, v[156:157]
	v_pk_add_f32 v[106:107], v[118:119], 0 op_sel_hi:[1,0]
	v_pk_add_f32 v[104:105], v[116:117], 0 op_sel_hi:[1,0]
	v_cvt_pk_bf16_f32 v104, v104, v105
	v_cvt_pk_bf16_f32 v105, v106, v107
	v_cvt_pk_bf16_f32 v106, v108, v109
	v_cvt_pk_bf16_f32 v107, v110, v111
	global_store_dwordx4 v[112:113], v[104:107], off
	v_cvt_pk_bf16_f32 v91, v90, v91
	v_cvt_pk_bf16_f32 v90, v88, v89
	v_cvt_pk_bf16_f32 v88, v96, v97
	v_cvt_pk_bf16_f32 v89, v98, v99
	global_store_dwordx4 v[112:113], v[88:91], off offset:256
	s_nop 1
	v_or_b32_e32 v88, 32, v152
	v_ashrrev_i32_e32 v89, 31, v88
	v_lshlrev_b64 v[88:89], 12, v[88:89]
	v_lshl_add_u64 v[88:89], s[58:59], 0, v[88:89]
	v_lshl_add_u64 v[96:97], v[88:89], 0, v[156:157]
	v_pk_add_f32 v[90:91], v[102:103], 0 op_sel_hi:[1,0]
	v_pk_add_f32 v[88:89], v[100:101], 0 op_sel_hi:[1,0]
	v_cvt_pk_bf16_f32 v88, v88, v89
	v_cvt_pk_bf16_f32 v89, v90, v91
	v_cvt_pk_bf16_f32 v90, v92, v93
	v_cvt_pk_bf16_f32 v91, v94, v95
	global_store_dwordx4 v[96:97], v[88:91], off
	v_cvt_pk_bf16_f32 v75, v74, v75
	v_cvt_pk_bf16_f32 v74, v72, v73
	v_cvt_pk_bf16_f32 v72, v80, v81
	v_cvt_pk_bf16_f32 v73, v82, v83
	global_store_dwordx4 v[96:97], v[72:75], off offset:256
	s_nop 1
	v_or_b32_e32 v72, 48, v152
	v_ashrrev_i32_e32 v73, 31, v72
	v_lshlrev_b64 v[72:73], 12, v[72:73]
	v_lshl_add_u64 v[72:73], s[58:59], 0, v[72:73]
	v_lshl_add_u64 v[80:81], v[72:73], 0, v[156:157]
	v_pk_add_f32 v[74:75], v[86:87], 0 op_sel_hi:[1,0]
	v_pk_add_f32 v[72:73], v[84:85], 0 op_sel_hi:[1,0]
	v_cvt_pk_bf16_f32 v72, v72, v73
	v_cvt_pk_bf16_f32 v73, v74, v75
	v_cvt_pk_bf16_f32 v74, v76, v77
	v_cvt_pk_bf16_f32 v75, v78, v79
	global_store_dwordx4 v[80:81], v[72:75], off
	s_nop 0
	s_mov_b32 s11, 0x80000
	v_pk_add_f32 v[72:73], v[66:67], 0 op_sel_hi:[1,0]
	v_pk_add_f32 v[66:67], v[64:65], 0 op_sel_hi:[1,0]
	v_cvt_pk_bf16_f32 v64, v68, v69
	v_cvt_pk_bf16_f32 v65, v70, v71
	v_cvt_pk_bf16_f32 v66, v66, v67
	v_cvt_pk_bf16_f32 v67, v72, v73
	global_store_dwordx4 v[80:81], v[64:67], off offset:256
	s_nop 0
	s_mov_b64 s[16:17], 0x80000
	v_pk_add_f32 v[66:67], v[58:59], 0 op_sel_hi:[1,0]
	v_pk_add_f32 v[58:59], v[56:57], 0 op_sel_hi:[1,0]
	v_cvt_pk_bf16_f32 v56, v60, v61
	v_add_co_u32_e32 v60, vcc, s11, v144
	v_cvt_pk_bf16_f32 v57, v62, v63
	v_cvt_pk_bf16_f32 v58, v58, v59
	v_cvt_pk_bf16_f32 v59, v66, v67
	v_addc_co_u32_e32 v61, vcc, 0, v145, vcc
	global_store_dwordx4 v[60:61], v[56:59], off
	s_nop 0
	v_lshl_add_u64 v[64:65], v[144:145], 0, s[16:17]
	v_pk_add_f32 v[56:57], v[42:43], 0 op_sel_hi:[1,0]
	v_pk_add_f32 v[42:43], v[40:41], 0 op_sel_hi:[1,0]
	v_cvt_pk_bf16_f32 v40, v48, v49
	v_cvt_pk_bf16_f32 v41, v50, v51
	v_cvt_pk_bf16_f32 v42, v42, v43
	v_cvt_pk_bf16_f32 v43, v56, v57
	global_store_dwordx4 v[64:65], v[40:43], off offset:256
	s_nop 0
	s_mov_b32 s11, 0x90000
	v_pk_add_f32 v[42:43], v[54:55], 0 op_sel_hi:[1,0]
	v_pk_add_f32 v[40:41], v[52:53], 0 op_sel_hi:[1,0]
	v_cvt_pk_bf16_f32 v40, v40, v41
	v_cvt_pk_bf16_f32 v41, v42, v43
	v_cvt_pk_bf16_f32 v42, v44, v45
	v_add_co_u32_e32 v44, vcc, s11, v144
	v_cvt_pk_bf16_f32 v43, v46, v47
	s_nop 0
	v_addc_co_u32_e32 v45, vcc, 0, v145, vcc
	s_mov_b64 s[16:17], 0x90000
	global_store_dwordx4 v[44:45], v[40:43], off
	s_nop 1
	v_pk_add_f32 v[40:41], v[26:27], 0 op_sel_hi:[1,0]
	v_pk_add_f32 v[26:27], v[24:25], 0 op_sel_hi:[1,0]
	v_lshl_add_u64 v[48:49], v[144:145], 0, s[16:17]
	v_cvt_pk_bf16_f32 v24, v32, v33
	v_cvt_pk_bf16_f32 v25, v34, v35
	v_cvt_pk_bf16_f32 v26, v26, v27
	v_cvt_pk_bf16_f32 v27, v40, v41
	global_store_dwordx4 v[48:49], v[24:27], off offset:256
	s_nop 0
	s_mov_b32 s11, 0xa0000
	v_pk_add_f32 v[26:27], v[38:39], 0 op_sel_hi:[1,0]
	v_pk_add_f32 v[24:25], v[36:37], 0 op_sel_hi:[1,0]
	v_cvt_pk_bf16_f32 v24, v24, v25
	v_cvt_pk_bf16_f32 v25, v26, v27
	v_cvt_pk_bf16_f32 v26, v28, v29
	v_add_co_u32_e32 v28, vcc, s11, v144
	v_cvt_pk_bf16_f32 v27, v30, v31
	s_nop 0
	v_addc_co_u32_e32 v29, vcc, 0, v145, vcc
	s_mov_b64 s[16:17], 0xa0000
	global_store_dwordx4 v[28:29], v[24:27], off
	s_nop 1
	v_pk_add_f32 v[24:25], v[10:11], 0 op_sel_hi:[1,0]
	v_pk_add_f32 v[10:11], v[8:9], 0 op_sel_hi:[1,0]
	v_lshl_add_u64 v[32:33], v[144:145], 0, s[16:17]
	v_cvt_pk_bf16_f32 v8, v16, v17
	v_cvt_pk_bf16_f32 v9, v18, v19
	v_cvt_pk_bf16_f32 v10, v10, v11
	v_cvt_pk_bf16_f32 v11, v24, v25
	global_store_dwordx4 v[32:33], v[8:11], off offset:256
	s_nop 0
	s_mov_b32 s11, 0xb0000
	v_pk_add_f32 v[10:11], v[22:23], 0 op_sel_hi:[1,0]
	v_pk_add_f32 v[8:9], v[20:21], 0 op_sel_hi:[1,0]
	v_cvt_pk_bf16_f32 v8, v8, v9
	v_cvt_pk_bf16_f32 v9, v10, v11
	v_cvt_pk_bf16_f32 v10, v12, v13
	v_add_co_u32_e32 v12, vcc, s11, v144
	v_cvt_pk_bf16_f32 v11, v14, v15
	s_nop 0
	v_addc_co_u32_e32 v13, vcc, 0, v145, vcc
	s_mov_b64 s[16:17], 0xb0000
	global_store_dwordx4 v[12:13], v[8:11], off
	s_nop 1
	v_pk_add_f32 v[8:9], v[2:3], 0 op_sel_hi:[1,0]
	v_pk_add_f32 v[2:3], v[0:1], 0 op_sel_hi:[1,0]
	v_lshl_add_u64 v[16:17], v[144:145], 0, s[16:17]
	v_cvt_pk_bf16_f32 v0, v4, v5
	v_cvt_pk_bf16_f32 v1, v6, v7
	v_cvt_pk_bf16_f32 v2, v2, v3
	v_cvt_pk_bf16_f32 v3, v8, v9
	s_andn2_b64 vcc, exec, s[2:3]
	s_mov_b64 s[2:3], -1
	global_store_dwordx4 v[16:17], v[0:3], off offset:256
	s_cbranch_vccnz .LBB0_275
	s_andn2_b64 vcc, exec, s[4:5]
	s_cbranch_vccnz .LBB0_274
	s_barrier
	s_branch .LBB0_274

.LBB0_434:
	v_lshl_or_b32 v146, s16, 8, v150
	v_lshl_add_u32 v158, s83, 8, v148
	v_ashrrev_i32_e32 v147, 31, v146
	v_mov_b64_e32 v[144:145], s[62:63]
	v_mad_i64_i32 v[154:155], s[16:17], v158, s80, v[144:145]
	v_lshlrev_b64 v[146:147], 1, v[146:147]
	v_pk_add_f32 v[156:157], v[122:123], 0 op_sel_hi:[1,0]
	v_pk_add_f32 v[122:123], v[120:121], 0 op_sel_hi:[1,0]
	v_lshl_add_u64 v[154:155], v[154:155], 0, v[146:147]
	v_cvt_pk_bf16_f32 v120, v124, v125
	v_cvt_pk_bf16_f32 v121, v126, v127
	v_cvt_pk_bf16_f32 v122, v122, v123
	v_cvt_pk_bf16_f32 v123, v156, v157
	global_store_dwordx4 v[154:155], v[120:123], off
	v_cvt_pk_bf16_f32 v107, v106, v107
	v_cvt_pk_bf16_f32 v106, v104, v105
	v_cvt_pk_bf16_f32 v104, v112, v113
	v_cvt_pk_bf16_f32 v105, v114, v115
	global_store_dwordx4 v[154:155], v[104:107], off offset:256
	s_nop 1
	v_or_b32_e32 v104, 16, v158
	v_mad_i64_i32 v[104:105], s[16:17], v104, s80, v[144:145]
	v_lshl_add_u64 v[112:113], v[104:105], 0, v[146:147]
	v_pk_add_f32 v[106:107], v[118:119], 0 op_sel_hi:[1,0]
	v_pk_add_f32 v[104:105], v[116:117], 0 op_sel_hi:[1,0]
	v_cvt_pk_bf16_f32 v104, v104, v105
	v_cvt_pk_bf16_f32 v105, v106, v107
	v_cvt_pk_bf16_f32 v106, v108, v109
	v_cvt_pk_bf16_f32 v107, v110, v111
	global_store_dwordx4 v[112:113], v[104:107], off
	v_cvt_pk_bf16_f32 v91, v90, v91
	v_cvt_pk_bf16_f32 v90, v88, v89
	v_cvt_pk_bf16_f32 v88, v96, v97
	v_cvt_pk_bf16_f32 v89, v98, v99
	global_store_dwordx4 v[112:113], v[88:91], off offset:256
	s_nop 1
	v_or_b32_e32 v88, 32, v158
	v_mad_i64_i32 v[88:89], s[16:17], v88, s80, v[144:145]
	v_lshl_add_u64 v[96:97], v[88:89], 0, v[146:147]
	v_pk_add_f32 v[90:91], v[102:103], 0 op_sel_hi:[1,0]
	v_pk_add_f32 v[88:89], v[100:101], 0 op_sel_hi:[1,0]
	v_cvt_pk_bf16_f32 v88, v88, v89
	v_cvt_pk_bf16_f32 v89, v90, v91
	v_cvt_pk_bf16_f32 v90, v92, v93
	v_cvt_pk_bf16_f32 v91, v94, v95
	global_store_dwordx4 v[96:97], v[88:91], off
	v_cvt_pk_bf16_f32 v75, v74, v75
	v_cvt_pk_bf16_f32 v74, v72, v73
	v_cvt_pk_bf16_f32 v72, v80, v81
	v_cvt_pk_bf16_f32 v73, v82, v83
	global_store_dwordx4 v[96:97], v[72:75], off offset:256
	s_nop 1
	v_or_b32_e32 v72, 48, v158
	v_mad_i64_i32 v[72:73], s[16:17], v72, s80, v[144:145]
	v_lshl_add_u64 v[80:81], v[72:73], 0, v[146:147]
	v_pk_add_f32 v[74:75], v[86:87], 0 op_sel_hi:[1,0]
	v_pk_add_f32 v[72:73], v[84:85], 0 op_sel_hi:[1,0]
	v_cvt_pk_bf16_f32 v72, v72, v73
	v_cvt_pk_bf16_f32 v73, v74, v75
	v_cvt_pk_bf16_f32 v74, v76, v77
	v_cvt_pk_bf16_f32 v75, v78, v79
	global_store_dwordx4 v[80:81], v[72:75], off
	v_cvt_pk_bf16_f32 v67, v66, v67
	v_cvt_pk_bf16_f32 v66, v64, v65
	v_cvt_pk_bf16_f32 v64, v68, v69
	v_cvt_pk_bf16_f32 v65, v70, v71
	global_store_dwordx4 v[80:81], v[64:67], off offset:256
	s_nop 1
	v_add_u32_e32 v64, 0x80, v158
	v_mad_i64_i32 v[64:65], s[16:17], v64, s80, v[144:145]
	v_pk_add_f32 v[66:67], v[58:59], 0 op_sel_hi:[1,0]
	v_pk_add_f32 v[58:59], v[56:57], 0 op_sel_hi:[1,0]
	v_lshl_add_u64 v[64:65], v[64:65], 0, v[146:147]
	v_cvt_pk_bf16_f32 v56, v60, v61
	v_cvt_pk_bf16_f32 v57, v62, v63
	v_cvt_pk_bf16_f32 v58, v58, v59
	v_cvt_pk_bf16_f32 v59, v66, v67
	global_store_dwordx4 v[64:65], v[56:59], off
	v_cvt_pk_bf16_f32 v43, v42, v43
	v_cvt_pk_bf16_f32 v42, v40, v41
	v_cvt_pk_bf16_f32 v40, v48, v49
	v_cvt_pk_bf16_f32 v41, v50, v51
	global_store_dwordx4 v[64:65], v[40:43], off offset:256
	s_nop 1
	v_add_u32_e32 v40, 0x90, v158
	v_mad_i64_i32 v[40:41], s[16:17], v40, s80, v[144:145]
	v_lshl_add_u64 v[48:49], v[40:41], 0, v[146:147]
	v_pk_add_f32 v[42:43], v[54:55], 0 op_sel_hi:[1,0]
	v_pk_add_f32 v[40:41], v[52:53], 0 op_sel_hi:[1,0]
	v_cvt_pk_bf16_f32 v40, v40, v41
	v_cvt_pk_bf16_f32 v41, v42, v43
	v_cvt_pk_bf16_f32 v42, v44, v45
	v_cvt_pk_bf16_f32 v43, v46, v47
	global_store_dwordx4 v[48:49], v[40:43], off
	v_cvt_pk_bf16_f32 v27, v26, v27
	v_cvt_pk_bf16_f32 v26, v24, v25
	v_cvt_pk_bf16_f32 v24, v32, v33
	v_cvt_pk_bf16_f32 v25, v34, v35
	global_store_dwordx4 v[48:49], v[24:27], off offset:256
	s_nop 1
	v_add_u32_e32 v24, 0xa0, v158
	v_mad_i64_i32 v[24:25], s[16:17], v24, s80, v[144:145]
	v_lshl_add_u64 v[32:33], v[24:25], 0, v[146:147]
	v_pk_add_f32 v[26:27], v[38:39], 0 op_sel_hi:[1,0]
	v_pk_add_f32 v[24:25], v[36:37], 0 op_sel_hi:[1,0]
	v_cvt_pk_bf16_f32 v24, v24, v25
	v_cvt_pk_bf16_f32 v25, v26, v27
	v_cvt_pk_bf16_f32 v26, v28, v29
	v_cvt_pk_bf16_f32 v27, v30, v31
	global_store_dwordx4 v[32:33], v[24:27], off
	s_nop 0
	s_and_b64 vcc, exec, s[2:3]
	v_pk_add_f32 v[24:25], v[10:11], 0 op_sel_hi:[1,0]
	v_pk_add_f32 v[10:11], v[8:9], 0 op_sel_hi:[1,0]
	v_cvt_pk_bf16_f32 v8, v16, v17
	v_cvt_pk_bf16_f32 v9, v18, v19
	v_cvt_pk_bf16_f32 v10, v10, v11
	v_cvt_pk_bf16_f32 v11, v24, v25
	global_store_dwordx4 v[32:33], v[8:11], off offset:256
	s_mov_b64 s[2:3], -1
	s_nop 0
	v_add_u32_e32 v8, 0xb0, v158
	v_mad_i64_i32 v[8:9], s[16:17], v8, s80, v[144:145]
	v_lshl_add_u64 v[16:17], v[8:9], 0, v[146:147]
	v_pk_add_f32 v[10:11], v[22:23], 0 op_sel_hi:[1,0]
	v_pk_add_f32 v[8:9], v[20:21], 0 op_sel_hi:[1,0]
	s_nop 0
	v_cvt_pk_bf16_f32 v8, v8, v9
	v_cvt_pk_bf16_f32 v9, v10, v11
	v_cvt_pk_bf16_f32 v10, v12, v13
	v_cvt_pk_bf16_f32 v11, v14, v15
	global_store_dwordx4 v[16:17], v[8:11], off
	s_nop 1
	v_pk_add_f32 v[8:9], v[2:3], 0 op_sel_hi:[1,0]
	v_pk_add_f32 v[2:3], v[0:1], 0 op_sel_hi:[1,0]
	v_cvt_pk_bf16_f32 v0, v4, v5
	v_cvt_pk_bf16_f32 v1, v6, v7
	v_cvt_pk_bf16_f32 v2, v2, v3
	v_cvt_pk_bf16_f32 v3, v8, v9
	global_store_dwordx4 v[16:17], v[0:3], off offset:256
	s_cbranch_vccnz .LBB0_423
	s_andn2_b64 vcc, exec, s[6:7]
	s_cbranch_vccnz .LBB0_422
	s_barrier
	s_branch .LBB0_422

.LBB0_1048:
	v_lshl_or_b32 v146, s16, 8, v150
	v_lshl_add_u32 v158, s38, 8, v148
	v_ashrrev_i32_e32 v147, 31, v146
	v_mov_b64_e32 v[144:145], s[58:59]
	v_mad_i64_i32 v[154:155], s[16:17], v158, s81, v[144:145]
	v_lshlrev_b64 v[146:147], 1, v[146:147]
	v_pk_add_f32 v[156:157], v[122:123], 0 op_sel_hi:[1,0]
	v_pk_add_f32 v[122:123], v[120:121], 0 op_sel_hi:[1,0]
	v_lshl_add_u64 v[154:155], v[154:155], 0, v[146:147]
	v_cvt_pk_bf16_f32 v120, v124, v125
	v_cvt_pk_bf16_f32 v121, v126, v127
	v_cvt_pk_bf16_f32 v122, v122, v123
	v_cvt_pk_bf16_f32 v123, v156, v157
	global_store_dwordx4 v[154:155], v[120:123], off
	v_cvt_pk_bf16_f32 v107, v106, v107
	v_cvt_pk_bf16_f32 v106, v104, v105
	v_cvt_pk_bf16_f32 v104, v112, v113
	v_cvt_pk_bf16_f32 v105, v114, v115
	global_store_dwordx4 v[154:155], v[104:107], off offset:256
	s_nop 1
	v_or_b32_e32 v104, 16, v158
	v_mad_i64_i32 v[104:105], s[16:17], v104, s81, v[144:145]
	v_lshl_add_u64 v[112:113], v[104:105], 0, v[146:147]
	v_pk_add_f32 v[106:107], v[118:119], 0 op_sel_hi:[1,0]
	v_pk_add_f32 v[104:105], v[116:117], 0 op_sel_hi:[1,0]
	v_cvt_pk_bf16_f32 v104, v104, v105
	v_cvt_pk_bf16_f32 v105, v106, v107
	v_cvt_pk_bf16_f32 v106, v108, v109
	v_cvt_pk_bf16_f32 v107, v110, v111
	global_store_dwordx4 v[112:113], v[104:107], off
	v_cvt_pk_bf16_f32 v91, v90, v91
	v_cvt_pk_bf16_f32 v90, v88, v89
	v_cvt_pk_bf16_f32 v88, v96, v97
	v_cvt_pk_bf16_f32 v89, v98, v99
	global_store_dwordx4 v[112:113], v[88:91], off offset:256
	s_nop 1
	v_or_b32_e32 v88, 32, v158
	v_mad_i64_i32 v[88:89], s[16:17], v88, s81, v[144:145]
	v_lshl_add_u64 v[96:97], v[88:89], 0, v[146:147]
	v_pk_add_f32 v[90:91], v[102:103], 0 op_sel_hi:[1,0]
	v_pk_add_f32 v[88:89], v[100:101], 0 op_sel_hi:[1,0]
	v_cvt_pk_bf16_f32 v88, v88, v89
	v_cvt_pk_bf16_f32 v89, v90, v91
	v_cvt_pk_bf16_f32 v90, v92, v93
	v_cvt_pk_bf16_f32 v91, v94, v95
	global_store_dwordx4 v[96:97], v[88:91], off
	v_cvt_pk_bf16_f32 v75, v74, v75
	v_cvt_pk_bf16_f32 v74, v72, v73
	v_cvt_pk_bf16_f32 v72, v80, v81
	v_cvt_pk_bf16_f32 v73, v82, v83
	global_store_dwordx4 v[96:97], v[72:75], off offset:256
	s_nop 1
	v_or_b32_e32 v72, 48, v158
	v_mad_i64_i32 v[72:73], s[16:17], v72, s81, v[144:145]
	v_lshl_add_u64 v[80:81], v[72:73], 0, v[146:147]
	v_pk_add_f32 v[74:75], v[86:87], 0 op_sel_hi:[1,0]
	v_pk_add_f32 v[72:73], v[84:85], 0 op_sel_hi:[1,0]
	v_cvt_pk_bf16_f32 v72, v72, v73
	v_cvt_pk_bf16_f32 v73, v74, v75
	v_cvt_pk_bf16_f32 v74, v76, v77
	v_cvt_pk_bf16_f32 v75, v78, v79
	global_store_dwordx4 v[80:81], v[72:75], off
	v_cvt_pk_bf16_f32 v67, v66, v67
	v_cvt_pk_bf16_f32 v66, v64, v65
	v_cvt_pk_bf16_f32 v64, v68, v69
	v_cvt_pk_bf16_f32 v65, v70, v71
	global_store_dwordx4 v[80:81], v[64:67], off offset:256
	s_nop 1
	v_add_u32_e32 v64, 0x80, v158
	v_mad_i64_i32 v[64:65], s[16:17], v64, s81, v[144:145]
	v_pk_add_f32 v[66:67], v[58:59], 0 op_sel_hi:[1,0]
	v_pk_add_f32 v[58:59], v[56:57], 0 op_sel_hi:[1,0]
	v_lshl_add_u64 v[64:65], v[64:65], 0, v[146:147]
	v_cvt_pk_bf16_f32 v56, v60, v61
	v_cvt_pk_bf16_f32 v57, v62, v63
	v_cvt_pk_bf16_f32 v58, v58, v59
	v_cvt_pk_bf16_f32 v59, v66, v67
	global_store_dwordx4 v[64:65], v[56:59], off
	v_cvt_pk_bf16_f32 v43, v42, v43
	v_cvt_pk_bf16_f32 v42, v40, v41
	v_cvt_pk_bf16_f32 v40, v48, v49
	v_cvt_pk_bf16_f32 v41, v50, v51
	global_store_dwordx4 v[64:65], v[40:43], off offset:256
	s_nop 1
	v_add_u32_e32 v40, 0x90, v158
	v_mad_i64_i32 v[40:41], s[16:17], v40, s81, v[144:145]
	v_lshl_add_u64 v[48:49], v[40:41], 0, v[146:147]
	v_pk_add_f32 v[42:43], v[54:55], 0 op_sel_hi:[1,0]
	v_pk_add_f32 v[40:41], v[52:53], 0 op_sel_hi:[1,0]
	v_cvt_pk_bf16_f32 v40, v40, v41
	v_cvt_pk_bf16_f32 v41, v42, v43
	v_cvt_pk_bf16_f32 v42, v44, v45
	v_cvt_pk_bf16_f32 v43, v46, v47
	global_store_dwordx4 v[48:49], v[40:43], off
	v_cvt_pk_bf16_f32 v27, v26, v27
	v_cvt_pk_bf16_f32 v26, v24, v25
	v_cvt_pk_bf16_f32 v24, v32, v33
	v_cvt_pk_bf16_f32 v25, v34, v35
	global_store_dwordx4 v[48:49], v[24:27], off offset:256
	s_nop 1
	v_add_u32_e32 v24, 0xa0, v158
	v_mad_i64_i32 v[24:25], s[16:17], v24, s81, v[144:145]
	v_lshl_add_u64 v[32:33], v[24:25], 0, v[146:147]
	v_pk_add_f32 v[26:27], v[38:39], 0 op_sel_hi:[1,0]
	v_pk_add_f32 v[24:25], v[36:37], 0 op_sel_hi:[1,0]
	v_cvt_pk_bf16_f32 v24, v24, v25
	v_cvt_pk_bf16_f32 v25, v26, v27
	v_cvt_pk_bf16_f32 v26, v28, v29
	v_cvt_pk_bf16_f32 v27, v30, v31
	global_store_dwordx4 v[32:33], v[24:27], off
	s_nop 0
	s_andn2_b64 vcc, exec, s[2:3]
	v_pk_add_f32 v[24:25], v[10:11], 0 op_sel_hi:[1,0]
	v_pk_add_f32 v[10:11], v[8:9], 0 op_sel_hi:[1,0]
	v_cvt_pk_bf16_f32 v8, v16, v17
	v_cvt_pk_bf16_f32 v9, v18, v19
	v_cvt_pk_bf16_f32 v10, v10, v11
	v_cvt_pk_bf16_f32 v11, v24, v25
	global_store_dwordx4 v[32:33], v[8:11], off offset:256
	s_mov_b64 s[2:3], -1
	s_nop 0
	v_add_u32_e32 v8, 0xb0, v158
	v_mad_i64_i32 v[8:9], s[16:17], v8, s81, v[144:145]
	v_lshl_add_u64 v[16:17], v[8:9], 0, v[146:147]
	v_pk_add_f32 v[10:11], v[22:23], 0 op_sel_hi:[1,0]
	v_pk_add_f32 v[8:9], v[20:21], 0 op_sel_hi:[1,0]
	s_nop 0
	v_cvt_pk_bf16_f32 v8, v8, v9
	v_cvt_pk_bf16_f32 v9, v10, v11
	v_cvt_pk_bf16_f32 v10, v12, v13
	v_cvt_pk_bf16_f32 v11, v14, v15
	global_store_dwordx4 v[16:17], v[8:11], off
	s_nop 1
	v_pk_add_f32 v[8:9], v[2:3], 0 op_sel_hi:[1,0]
	v_pk_add_f32 v[2:3], v[0:1], 0 op_sel_hi:[1,0]
	v_cvt_pk_bf16_f32 v0, v4, v5
	v_cvt_pk_bf16_f32 v1, v6, v7
	v_cvt_pk_bf16_f32 v2, v2, v3
	v_cvt_pk_bf16_f32 v3, v8, v9
	global_store_dwordx4 v[16:17], v[0:3], off offset:256
	s_cbranch_vccnz .LBB0_1041
	s_andn2_b64 vcc, exec, s[0:1]
	s_cbranch_vccnz .LBB0_1040
	s_barrier
	s_branch .LBB0_1040

.LBB0_1184:
	v_lshl_or_b32 v146, s16, 8, v150
	v_lshl_add_u32 v158, s38, 8, v148
	v_add_u32_e32 v154, 0xffffbc00, v158
	v_ashrrev_i32_e32 v147, 31, v146
	v_mov_b64_e32 v[144:145], s[58:59]
	v_mad_i64_i32 v[154:155], s[16:17], v154, s83, v[144:145]
	v_lshlrev_b64 v[146:147], 1, v[146:147]
	v_pk_add_f32 v[156:157], v[122:123], 0 op_sel_hi:[1,0]
	v_pk_add_f32 v[122:123], v[120:121], 0 op_sel_hi:[1,0]
	v_lshl_add_u64 v[154:155], v[154:155], 0, v[146:147]
	v_cvt_pk_bf16_f32 v120, v124, v125
	v_cvt_pk_bf16_f32 v121, v126, v127
	v_cvt_pk_bf16_f32 v122, v122, v123
	v_cvt_pk_bf16_f32 v123, v156, v157
	global_store_dwordx4 v[154:155], v[120:123], off
	v_cvt_pk_bf16_f32 v107, v106, v107
	v_cvt_pk_bf16_f32 v106, v104, v105
	v_cvt_pk_bf16_f32 v104, v112, v113
	v_cvt_pk_bf16_f32 v105, v114, v115
	global_store_dwordx4 v[154:155], v[104:107], off offset:256
	s_nop 1
	v_add_u32_e32 v104, 0xffffbc10, v158
	v_mad_i64_i32 v[104:105], s[16:17], v104, s83, v[144:145]
	v_lshl_add_u64 v[112:113], v[104:105], 0, v[146:147]
	v_pk_add_f32 v[106:107], v[118:119], 0 op_sel_hi:[1,0]
	v_pk_add_f32 v[104:105], v[116:117], 0 op_sel_hi:[1,0]
	v_cvt_pk_bf16_f32 v104, v104, v105
	v_cvt_pk_bf16_f32 v105, v106, v107
	v_cvt_pk_bf16_f32 v106, v108, v109
	v_cvt_pk_bf16_f32 v107, v110, v111
	global_store_dwordx4 v[112:113], v[104:107], off
	v_cvt_pk_bf16_f32 v91, v90, v91
	v_cvt_pk_bf16_f32 v90, v88, v89
	v_cvt_pk_bf16_f32 v88, v96, v97
	v_cvt_pk_bf16_f32 v89, v98, v99
	global_store_dwordx4 v[112:113], v[88:91], off offset:256
	s_nop 1
	v_add_u32_e32 v88, 0xffffbc20, v158
	v_mad_i64_i32 v[88:89], s[16:17], v88, s83, v[144:145]
	v_lshl_add_u64 v[96:97], v[88:89], 0, v[146:147]
	v_pk_add_f32 v[90:91], v[102:103], 0 op_sel_hi:[1,0]
	v_pk_add_f32 v[88:89], v[100:101], 0 op_sel_hi:[1,0]
	v_cvt_pk_bf16_f32 v88, v88, v89
	v_cvt_pk_bf16_f32 v89, v90, v91
	v_cvt_pk_bf16_f32 v90, v92, v93
	v_cvt_pk_bf16_f32 v91, v94, v95
	global_store_dwordx4 v[96:97], v[88:91], off
	v_cvt_pk_bf16_f32 v75, v74, v75
	v_cvt_pk_bf16_f32 v74, v72, v73
	v_cvt_pk_bf16_f32 v72, v80, v81
	v_cvt_pk_bf16_f32 v73, v82, v83
	global_store_dwordx4 v[96:97], v[72:75], off offset:256
	s_nop 1
	v_add_u32_e32 v72, 0xffffbc30, v158
	v_mad_i64_i32 v[72:73], s[16:17], v72, s83, v[144:145]
	v_lshl_add_u64 v[80:81], v[72:73], 0, v[146:147]
	v_pk_add_f32 v[74:75], v[86:87], 0 op_sel_hi:[1,0]
	v_pk_add_f32 v[72:73], v[84:85], 0 op_sel_hi:[1,0]
	v_cvt_pk_bf16_f32 v72, v72, v73
	v_cvt_pk_bf16_f32 v73, v74, v75
	v_cvt_pk_bf16_f32 v74, v76, v77
	v_cvt_pk_bf16_f32 v75, v78, v79
	global_store_dwordx4 v[80:81], v[72:75], off
	v_cvt_pk_bf16_f32 v67, v66, v67
	v_cvt_pk_bf16_f32 v66, v64, v65
	v_cvt_pk_bf16_f32 v64, v68, v69
	v_cvt_pk_bf16_f32 v65, v70, v71
	global_store_dwordx4 v[80:81], v[64:67], off offset:256
	s_nop 1
	v_add_u32_e32 v64, 0xffffbc80, v158
	v_mad_i64_i32 v[64:65], s[16:17], v64, s83, v[144:145]
	v_pk_add_f32 v[66:67], v[58:59], 0 op_sel_hi:[1,0]
	v_pk_add_f32 v[58:59], v[56:57], 0 op_sel_hi:[1,0]
	v_lshl_add_u64 v[64:65], v[64:65], 0, v[146:147]
	v_cvt_pk_bf16_f32 v56, v60, v61
	v_cvt_pk_bf16_f32 v57, v62, v63
	v_cvt_pk_bf16_f32 v58, v58, v59
	v_cvt_pk_bf16_f32 v59, v66, v67
	global_store_dwordx4 v[64:65], v[56:59], off
	v_cvt_pk_bf16_f32 v43, v42, v43
	v_cvt_pk_bf16_f32 v42, v40, v41
	v_cvt_pk_bf16_f32 v40, v48, v49
	v_cvt_pk_bf16_f32 v41, v50, v51
	global_store_dwordx4 v[64:65], v[40:43], off offset:256
	s_nop 1
	v_add_u32_e32 v40, 0xffffbc90, v158
	v_mad_i64_i32 v[40:41], s[16:17], v40, s83, v[144:145]
	v_lshl_add_u64 v[48:49], v[40:41], 0, v[146:147]
	v_pk_add_f32 v[42:43], v[54:55], 0 op_sel_hi:[1,0]
	v_pk_add_f32 v[40:41], v[52:53], 0 op_sel_hi:[1,0]
	v_cvt_pk_bf16_f32 v40, v40, v41
	v_cvt_pk_bf16_f32 v41, v42, v43
	v_cvt_pk_bf16_f32 v42, v44, v45
	v_cvt_pk_bf16_f32 v43, v46, v47
	global_store_dwordx4 v[48:49], v[40:43], off
	v_cvt_pk_bf16_f32 v27, v26, v27
	v_cvt_pk_bf16_f32 v26, v24, v25
	v_cvt_pk_bf16_f32 v24, v32, v33
	v_cvt_pk_bf16_f32 v25, v34, v35
	global_store_dwordx4 v[48:49], v[24:27], off offset:256
	s_nop 1
	v_add_u32_e32 v24, 0xffffbca0, v158
	v_mad_i64_i32 v[24:25], s[16:17], v24, s83, v[144:145]
	v_lshl_add_u64 v[32:33], v[24:25], 0, v[146:147]
	v_pk_add_f32 v[26:27], v[38:39], 0 op_sel_hi:[1,0]
	v_pk_add_f32 v[24:25], v[36:37], 0 op_sel_hi:[1,0]
	v_cvt_pk_bf16_f32 v24, v24, v25
	v_cvt_pk_bf16_f32 v25, v26, v27
	v_cvt_pk_bf16_f32 v26, v28, v29
	v_cvt_pk_bf16_f32 v27, v30, v31
	global_store_dwordx4 v[32:33], v[24:27], off
	s_nop 0
	s_andn2_b64 vcc, exec, s[2:3]
	v_pk_add_f32 v[24:25], v[10:11], 0 op_sel_hi:[1,0]
	v_pk_add_f32 v[10:11], v[8:9], 0 op_sel_hi:[1,0]
	v_cvt_pk_bf16_f32 v8, v16, v17
	v_cvt_pk_bf16_f32 v9, v18, v19
	v_cvt_pk_bf16_f32 v10, v10, v11
	v_cvt_pk_bf16_f32 v11, v24, v25
	global_store_dwordx4 v[32:33], v[8:11], off offset:256
	s_mov_b64 s[2:3], -1
	s_nop 0
	v_add_u32_e32 v8, 0xffffbcb0, v158
	v_mad_i64_i32 v[8:9], s[16:17], v8, s83, v[144:145]
	v_lshl_add_u64 v[16:17], v[8:9], 0, v[146:147]
	v_pk_add_f32 v[10:11], v[22:23], 0 op_sel_hi:[1,0]
	v_pk_add_f32 v[8:9], v[20:21], 0 op_sel_hi:[1,0]
	s_nop 0
	v_cvt_pk_bf16_f32 v8, v8, v9
	v_cvt_pk_bf16_f32 v9, v10, v11
	v_cvt_pk_bf16_f32 v10, v12, v13
	v_cvt_pk_bf16_f32 v11, v14, v15
	global_store_dwordx4 v[16:17], v[8:11], off
	s_nop 1
	v_pk_add_f32 v[8:9], v[2:3], 0 op_sel_hi:[1,0]
	v_pk_add_f32 v[2:3], v[0:1], 0 op_sel_hi:[1,0]
	v_cvt_pk_bf16_f32 v0, v4, v5
	v_cvt_pk_bf16_f32 v1, v6, v7
	v_cvt_pk_bf16_f32 v2, v2, v3
	v_cvt_pk_bf16_f32 v3, v8, v9
	global_store_dwordx4 v[16:17], v[0:3], off offset:256
	s_cbranch_vccnz .LBB0_1177
	s_andn2_b64 vcc, exec, s[4:5]
	s_cbranch_vccnz .LBB0_1176
	s_barrier
	s_branch .LBB0_1176

.LBB0_1529:
	v_lshl_add_u32 v152, s28, 8, v146
	v_lshl_or_b32 v144, s20, 8, v148
	v_ashrrev_i32_e32 v153, 31, v152
	v_ashrrev_i32_e32 v145, 31, v144
	v_lshlrev_b64 v[154:155], 12, v[152:153]
	v_lshl_add_u64 v[154:155], s[58:59], 0, v[154:155]
	v_lshlrev_b64 v[156:157], 1, v[144:145]
	v_lshl_add_u64 v[144:145], v[154:155], 0, v[156:157]
	v_cvt_pk_bf16_f32 v123, v122, v123
	v_cvt_pk_bf16_f32 v122, v120, v121
	v_cvt_pk_bf16_f32 v120, v124, v125
	v_cvt_pk_bf16_f32 v121, v126, v127
	global_store_dwordx4 v[144:145], v[120:123], off
	v_cvt_pk_bf16_f32 v107, v106, v107
	v_cvt_pk_bf16_f32 v106, v104, v105
	v_cvt_pk_bf16_f32 v104, v112, v113
	v_cvt_pk_bf16_f32 v105, v114, v115
	global_store_dwordx4 v[144:145], v[104:107], off offset:256
	s_nop 1
	v_or_b32_e32 v104, 16, v152
	v_ashrrev_i32_e32 v105, 31, v104
	v_lshlrev_b64 v[104:105], 12, v[104:105]
	v_lshl_add_u64 v[104:105], s[58:59], 0, v[104:105]
	v_lshl_add_u64 v[112:113], v[104:105], 0, v[156:157]
	v_pk_add_f32 v[106:107], v[118:119], 0 op_sel_hi:[1,0]
	v_pk_add_f32 v[104:105], v[116:117], 0 op_sel_hi:[1,0]
	v_cvt_pk_bf16_f32 v104, v104, v105
	v_cvt_pk_bf16_f32 v105, v106, v107
	v_cvt_pk_bf16_f32 v106, v108, v109
	v_cvt_pk_bf16_f32 v107, v110, v111
	global_store_dwordx4 v[112:113], v[104:107], off
	v_cvt_pk_bf16_f32 v91, v90, v91
	v_cvt_pk_bf16_f32 v90, v88, v89
	v_cvt_pk_bf16_f32 v88, v96, v97
	v_cvt_pk_bf16_f32 v89, v98, v99
	global_store_dwordx4 v[112:113], v[88:91], off offset:256
	s_nop 1
	v_or_b32_e32 v88, 32, v152
	v_ashrrev_i32_e32 v89, 31, v88
	v_lshlrev_b64 v[88:89], 12, v[88:89]
	v_lshl_add_u64 v[88:89], s[58:59], 0, v[88:89]
	v_lshl_add_u64 v[96:97], v[88:89], 0, v[156:157]
	v_pk_add_f32 v[90:91], v[102:103], 0 op_sel_hi:[1,0]
	v_pk_add_f32 v[88:89], v[100:101], 0 op_sel_hi:[1,0]
	v_cvt_pk_bf16_f32 v88, v88, v89
	v_cvt_pk_bf16_f32 v89, v90, v91
	v_cvt_pk_bf16_f32 v90, v92, v93
	v_cvt_pk_bf16_f32 v91, v94, v95
	global_store_dwordx4 v[96:97], v[88:91], off
	v_cvt_pk_bf16_f32 v75, v74, v75
	v_cvt_pk_bf16_f32 v74, v72, v73
	v_cvt_pk_bf16_f32 v72, v80, v81
	v_cvt_pk_bf16_f32 v73, v82, v83
	global_store_dwordx4 v[96:97], v[72:75], off offset:256
	s_nop 1
	v_or_b32_e32 v72, 48, v152
	v_ashrrev_i32_e32 v73, 31, v72
	v_lshlrev_b64 v[72:73], 12, v[72:73]
	v_lshl_add_u64 v[72:73], s[58:59], 0, v[72:73]
	v_lshl_add_u64 v[80:81], v[72:73], 0, v[156:157]
	v_pk_add_f32 v[74:75], v[86:87], 0 op_sel_hi:[1,0]
	v_pk_add_f32 v[72:73], v[84:85], 0 op_sel_hi:[1,0]
	v_cvt_pk_bf16_f32 v72, v72, v73
	v_cvt_pk_bf16_f32 v73, v74, v75
	v_cvt_pk_bf16_f32 v74, v76, v77
	v_cvt_pk_bf16_f32 v75, v78, v79
	global_store_dwordx4 v[80:81], v[72:75], off
	s_nop 0
	s_mov_b32 s15, 0x80000
	v_pk_add_f32 v[72:73], v[66:67], 0 op_sel_hi:[1,0]
	v_pk_add_f32 v[66:67], v[64:65], 0 op_sel_hi:[1,0]
	v_cvt_pk_bf16_f32 v64, v68, v69
	v_cvt_pk_bf16_f32 v65, v70, v71
	v_cvt_pk_bf16_f32 v66, v66, v67
	v_cvt_pk_bf16_f32 v67, v72, v73
	global_store_dwordx4 v[80:81], v[64:67], off offset:256
	s_nop 0
	s_mov_b64 s[20:21], 0x80000
	v_pk_add_f32 v[66:67], v[58:59], 0 op_sel_hi:[1,0]
	v_pk_add_f32 v[58:59], v[56:57], 0 op_sel_hi:[1,0]
	v_cvt_pk_bf16_f32 v56, v60, v61
	v_add_co_u32_e32 v60, vcc, s15, v144
	v_cvt_pk_bf16_f32 v57, v62, v63
	v_cvt_pk_bf16_f32 v58, v58, v59
	v_cvt_pk_bf16_f32 v59, v66, v67
	v_addc_co_u32_e32 v61, vcc, 0, v145, vcc
	global_store_dwordx4 v[60:61], v[56:59], off
	s_nop 0
	v_lshl_add_u64 v[64:65], v[144:145], 0, s[20:21]
	v_pk_add_f32 v[56:57], v[42:43], 0 op_sel_hi:[1,0]
	v_pk_add_f32 v[42:43], v[40:41], 0 op_sel_hi:[1,0]
	v_cvt_pk_bf16_f32 v40, v48, v49
	v_cvt_pk_bf16_f32 v41, v50, v51
	v_cvt_pk_bf16_f32 v42, v42, v43
	v_cvt_pk_bf16_f32 v43, v56, v57
	global_store_dwordx4 v[64:65], v[40:43], off offset:256
	s_nop 0
	s_mov_b32 s15, 0x90000
	v_pk_add_f32 v[42:43], v[54:55], 0 op_sel_hi:[1,0]
	v_pk_add_f32 v[40:41], v[52:53], 0 op_sel_hi:[1,0]
	v_cvt_pk_bf16_f32 v40, v40, v41
	v_cvt_pk_bf16_f32 v41, v42, v43
	v_cvt_pk_bf16_f32 v42, v44, v45
	v_add_co_u32_e32 v44, vcc, s15, v144
	v_cvt_pk_bf16_f32 v43, v46, v47
	s_nop 0
	v_addc_co_u32_e32 v45, vcc, 0, v145, vcc
	s_mov_b64 s[20:21], 0x90000
	global_store_dwordx4 v[44:45], v[40:43], off
	s_nop 1
	v_pk_add_f32 v[40:41], v[26:27], 0 op_sel_hi:[1,0]
	v_pk_add_f32 v[26:27], v[24:25], 0 op_sel_hi:[1,0]
	v_lshl_add_u64 v[48:49], v[144:145], 0, s[20:21]
	v_cvt_pk_bf16_f32 v24, v32, v33
	v_cvt_pk_bf16_f32 v25, v34, v35
	v_cvt_pk_bf16_f32 v26, v26, v27
	v_cvt_pk_bf16_f32 v27, v40, v41
	global_store_dwordx4 v[48:49], v[24:27], off offset:256
	s_nop 0
	s_mov_b32 s15, 0xa0000
	v_pk_add_f32 v[26:27], v[38:39], 0 op_sel_hi:[1,0]
	v_pk_add_f32 v[24:25], v[36:37], 0 op_sel_hi:[1,0]
	v_cvt_pk_bf16_f32 v24, v24, v25
	v_cvt_pk_bf16_f32 v25, v26, v27
	v_cvt_pk_bf16_f32 v26, v28, v29
	v_add_co_u32_e32 v28, vcc, s15, v144
	v_cvt_pk_bf16_f32 v27, v30, v31
	s_nop 0
	v_addc_co_u32_e32 v29, vcc, 0, v145, vcc
	s_mov_b64 s[20:21], 0xa0000
	global_store_dwordx4 v[28:29], v[24:27], off
	s_nop 1
	v_pk_add_f32 v[24:25], v[10:11], 0 op_sel_hi:[1,0]
	v_pk_add_f32 v[10:11], v[8:9], 0 op_sel_hi:[1,0]
	v_lshl_add_u64 v[32:33], v[144:145], 0, s[20:21]
	v_cvt_pk_bf16_f32 v8, v16, v17
	v_cvt_pk_bf16_f32 v9, v18, v19
	v_cvt_pk_bf16_f32 v10, v10, v11
	v_cvt_pk_bf16_f32 v11, v24, v25
	global_store_dwordx4 v[32:33], v[8:11], off offset:256
	s_nop 0
	s_mov_b32 s15, 0xb0000
	v_pk_add_f32 v[10:11], v[22:23], 0 op_sel_hi:[1,0]
	v_pk_add_f32 v[8:9], v[20:21], 0 op_sel_hi:[1,0]
	v_cvt_pk_bf16_f32 v8, v8, v9
	v_cvt_pk_bf16_f32 v9, v10, v11
	v_cvt_pk_bf16_f32 v10, v12, v13
	v_add_co_u32_e32 v12, vcc, s15, v144
	v_cvt_pk_bf16_f32 v11, v14, v15
	s_nop 0
	v_addc_co_u32_e32 v13, vcc, 0, v145, vcc
	s_mov_b64 s[20:21], 0xb0000
	global_store_dwordx4 v[12:13], v[8:11], off
	s_nop 1
	v_pk_add_f32 v[8:9], v[2:3], 0 op_sel_hi:[1,0]
	v_pk_add_f32 v[2:3], v[0:1], 0 op_sel_hi:[1,0]
	v_lshl_add_u64 v[16:17], v[144:145], 0, s[20:21]
	v_cvt_pk_bf16_f32 v0, v4, v5
	v_cvt_pk_bf16_f32 v1, v6, v7
	v_cvt_pk_bf16_f32 v2, v2, v3
	v_cvt_pk_bf16_f32 v3, v8, v9
	s_andn2_b64 vcc, exec, s[2:3]
	s_mov_b64 s[2:3], -1
	global_store_dwordx4 v[16:17], v[0:3], off offset:256
	s_cbranch_vccnz .LBB0_1522
	s_andn2_b64 vcc, exec, s[4:5]
	s_cbranch_vccnz .LBB0_1521
	s_barrier
	s_branch .LBB0_1521

.LBB0_1681:
	v_lshl_or_b32 v146, s20, 8, v150
	v_lshl_add_u32 v158, s51, 8, v148
	v_ashrrev_i32_e32 v147, 31, v146
	v_mov_b64_e32 v[144:145], s[62:63]
	v_mad_i64_i32 v[154:155], s[18:19], v158, s48, v[144:145]
	v_lshlrev_b64 v[146:147], 1, v[146:147]
	v_pk_add_f32 v[156:157], v[122:123], 0 op_sel_hi:[1,0]
	v_pk_add_f32 v[122:123], v[120:121], 0 op_sel_hi:[1,0]
	v_lshl_add_u64 v[154:155], v[154:155], 0, v[146:147]
	v_cvt_pk_bf16_f32 v120, v124, v125
	v_cvt_pk_bf16_f32 v121, v126, v127
	v_cvt_pk_bf16_f32 v122, v122, v123
	v_cvt_pk_bf16_f32 v123, v156, v157
	global_store_dwordx4 v[154:155], v[120:123], off
	v_cvt_pk_bf16_f32 v107, v106, v107
	v_cvt_pk_bf16_f32 v106, v104, v105
	v_cvt_pk_bf16_f32 v104, v112, v113
	v_cvt_pk_bf16_f32 v105, v114, v115
	global_store_dwordx4 v[154:155], v[104:107], off offset:256
	s_nop 1
	v_or_b32_e32 v104, 16, v158
	v_mad_i64_i32 v[104:105], s[18:19], v104, s48, v[144:145]
	v_lshl_add_u64 v[112:113], v[104:105], 0, v[146:147]
	v_pk_add_f32 v[106:107], v[118:119], 0 op_sel_hi:[1,0]
	v_pk_add_f32 v[104:105], v[116:117], 0 op_sel_hi:[1,0]
	v_cvt_pk_bf16_f32 v104, v104, v105
	v_cvt_pk_bf16_f32 v105, v106, v107
	v_cvt_pk_bf16_f32 v106, v108, v109
	v_cvt_pk_bf16_f32 v107, v110, v111
	global_store_dwordx4 v[112:113], v[104:107], off
	v_cvt_pk_bf16_f32 v91, v90, v91
	v_cvt_pk_bf16_f32 v90, v88, v89
	v_cvt_pk_bf16_f32 v88, v96, v97
	v_cvt_pk_bf16_f32 v89, v98, v99
	global_store_dwordx4 v[112:113], v[88:91], off offset:256
	s_nop 1
	v_or_b32_e32 v88, 32, v158
	v_mad_i64_i32 v[88:89], s[18:19], v88, s48, v[144:145]
	v_lshl_add_u64 v[96:97], v[88:89], 0, v[146:147]
	v_pk_add_f32 v[90:91], v[102:103], 0 op_sel_hi:[1,0]
	v_pk_add_f32 v[88:89], v[100:101], 0 op_sel_hi:[1,0]
	v_cvt_pk_bf16_f32 v88, v88, v89
	v_cvt_pk_bf16_f32 v89, v90, v91
	v_cvt_pk_bf16_f32 v90, v92, v93
	v_cvt_pk_bf16_f32 v91, v94, v95
	global_store_dwordx4 v[96:97], v[88:91], off
	v_cvt_pk_bf16_f32 v75, v74, v75
	v_cvt_pk_bf16_f32 v74, v72, v73
	v_cvt_pk_bf16_f32 v72, v80, v81
	v_cvt_pk_bf16_f32 v73, v82, v83
	global_store_dwordx4 v[96:97], v[72:75], off offset:256
	s_nop 1
	v_or_b32_e32 v72, 48, v158
	v_mad_i64_i32 v[72:73], s[18:19], v72, s48, v[144:145]
	v_lshl_add_u64 v[80:81], v[72:73], 0, v[146:147]
	v_pk_add_f32 v[74:75], v[86:87], 0 op_sel_hi:[1,0]
	v_pk_add_f32 v[72:73], v[84:85], 0 op_sel_hi:[1,0]
	v_cvt_pk_bf16_f32 v72, v72, v73
	v_cvt_pk_bf16_f32 v73, v74, v75
	v_cvt_pk_bf16_f32 v74, v76, v77
	v_cvt_pk_bf16_f32 v75, v78, v79
	global_store_dwordx4 v[80:81], v[72:75], off
	v_cvt_pk_bf16_f32 v67, v66, v67
	v_cvt_pk_bf16_f32 v66, v64, v65
	v_cvt_pk_bf16_f32 v64, v68, v69
	v_cvt_pk_bf16_f32 v65, v70, v71
	global_store_dwordx4 v[80:81], v[64:67], off offset:256
	s_nop 1
	v_add_u32_e32 v64, 0x80, v158
	v_mad_i64_i32 v[64:65], s[18:19], v64, s48, v[144:145]
	v_pk_add_f32 v[66:67], v[58:59], 0 op_sel_hi:[1,0]
	v_pk_add_f32 v[58:59], v[56:57], 0 op_sel_hi:[1,0]
	v_lshl_add_u64 v[64:65], v[64:65], 0, v[146:147]
	v_cvt_pk_bf16_f32 v56, v60, v61
	v_cvt_pk_bf16_f32 v57, v62, v63
	v_cvt_pk_bf16_f32 v58, v58, v59
	v_cvt_pk_bf16_f32 v59, v66, v67
	global_store_dwordx4 v[64:65], v[56:59], off
	v_cvt_pk_bf16_f32 v43, v42, v43
	v_cvt_pk_bf16_f32 v42, v40, v41
	v_cvt_pk_bf16_f32 v40, v48, v49
	v_cvt_pk_bf16_f32 v41, v50, v51
	global_store_dwordx4 v[64:65], v[40:43], off offset:256
	s_nop 1
	v_add_u32_e32 v40, 0x90, v158
	v_mad_i64_i32 v[40:41], s[18:19], v40, s48, v[144:145]
	v_lshl_add_u64 v[48:49], v[40:41], 0, v[146:147]
	v_pk_add_f32 v[42:43], v[54:55], 0 op_sel_hi:[1,0]
	v_pk_add_f32 v[40:41], v[52:53], 0 op_sel_hi:[1,0]
	v_cvt_pk_bf16_f32 v40, v40, v41
	v_cvt_pk_bf16_f32 v41, v42, v43
	v_cvt_pk_bf16_f32 v42, v44, v45
	v_cvt_pk_bf16_f32 v43, v46, v47
	global_store_dwordx4 v[48:49], v[40:43], off
	v_cvt_pk_bf16_f32 v27, v26, v27
	v_cvt_pk_bf16_f32 v26, v24, v25
	v_cvt_pk_bf16_f32 v24, v32, v33
	v_cvt_pk_bf16_f32 v25, v34, v35
	global_store_dwordx4 v[48:49], v[24:27], off offset:256
	s_nop 1
	v_add_u32_e32 v24, 0xa0, v158
	v_mad_i64_i32 v[24:25], s[18:19], v24, s48, v[144:145]
	v_lshl_add_u64 v[32:33], v[24:25], 0, v[146:147]
	v_pk_add_f32 v[26:27], v[38:39], 0 op_sel_hi:[1,0]
	v_pk_add_f32 v[24:25], v[36:37], 0 op_sel_hi:[1,0]
	v_cvt_pk_bf16_f32 v24, v24, v25
	v_cvt_pk_bf16_f32 v25, v26, v27
	v_cvt_pk_bf16_f32 v26, v28, v29
	v_cvt_pk_bf16_f32 v27, v30, v31
	global_store_dwordx4 v[32:33], v[24:27], off
	s_nop 0
	s_and_b64 vcc, exec, s[2:3]
	v_pk_add_f32 v[24:25], v[10:11], 0 op_sel_hi:[1,0]
	v_pk_add_f32 v[10:11], v[8:9], 0 op_sel_hi:[1,0]
	v_cvt_pk_bf16_f32 v8, v16, v17
	v_cvt_pk_bf16_f32 v9, v18, v19
	v_cvt_pk_bf16_f32 v10, v10, v11
	v_cvt_pk_bf16_f32 v11, v24, v25
	global_store_dwordx4 v[32:33], v[8:11], off offset:256
	s_mov_b64 s[2:3], -1
	s_nop 0
	v_add_u32_e32 v8, 0xb0, v158
	v_mad_i64_i32 v[8:9], s[18:19], v8, s48, v[144:145]
	v_lshl_add_u64 v[16:17], v[8:9], 0, v[146:147]
	v_pk_add_f32 v[10:11], v[22:23], 0 op_sel_hi:[1,0]
	v_pk_add_f32 v[8:9], v[20:21], 0 op_sel_hi:[1,0]
	s_nop 0
	v_cvt_pk_bf16_f32 v8, v8, v9
	v_cvt_pk_bf16_f32 v9, v10, v11
	v_cvt_pk_bf16_f32 v10, v12, v13
	v_cvt_pk_bf16_f32 v11, v14, v15
	global_store_dwordx4 v[16:17], v[8:11], off
	s_nop 1
	v_pk_add_f32 v[8:9], v[2:3], 0 op_sel_hi:[1,0]
	v_pk_add_f32 v[2:3], v[0:1], 0 op_sel_hi:[1,0]
	v_cvt_pk_bf16_f32 v0, v4, v5
	v_cvt_pk_bf16_f32 v1, v6, v7
	v_cvt_pk_bf16_f32 v2, v2, v3
	v_cvt_pk_bf16_f32 v3, v8, v9
	global_store_dwordx4 v[16:17], v[0:3], off offset:256
	s_cbranch_vccnz .LBB0_1670
	s_andn2_b64 vcc, exec, s[0:1]
	s_cbranch_vccnz .LBB0_1669
	s_barrier
	s_branch .LBB0_1669

.LBB0_2293:
	v_lshl_or_b32 v146, s24, 8, v150
	v_lshl_add_u32 v158, s22, 8, v148
	v_ashrrev_i32_e32 v147, 31, v146
	v_mov_b64_e32 v[144:145], s[58:59]
	v_mad_i64_i32 v[154:155], s[24:25], v158, s49, v[144:145]
	v_lshlrev_b64 v[146:147], 1, v[146:147]
	v_pk_add_f32 v[156:157], v[122:123], 0 op_sel_hi:[1,0]
	v_pk_add_f32 v[122:123], v[120:121], 0 op_sel_hi:[1,0]
	v_lshl_add_u64 v[154:155], v[154:155], 0, v[146:147]
	v_cvt_pk_bf16_f32 v120, v124, v125
	v_cvt_pk_bf16_f32 v121, v126, v127
	v_cvt_pk_bf16_f32 v122, v122, v123
	v_cvt_pk_bf16_f32 v123, v156, v157
	global_store_dwordx4 v[154:155], v[120:123], off
	v_cvt_pk_bf16_f32 v107, v106, v107
	v_cvt_pk_bf16_f32 v106, v104, v105
	v_cvt_pk_bf16_f32 v104, v112, v113
	v_cvt_pk_bf16_f32 v105, v114, v115
	global_store_dwordx4 v[154:155], v[104:107], off offset:256
	s_nop 1
	v_or_b32_e32 v104, 16, v158
	v_mad_i64_i32 v[104:105], s[24:25], v104, s49, v[144:145]
	v_lshl_add_u64 v[112:113], v[104:105], 0, v[146:147]
	v_pk_add_f32 v[106:107], v[118:119], 0 op_sel_hi:[1,0]
	v_pk_add_f32 v[104:105], v[116:117], 0 op_sel_hi:[1,0]
	v_cvt_pk_bf16_f32 v104, v104, v105
	v_cvt_pk_bf16_f32 v105, v106, v107
	v_cvt_pk_bf16_f32 v106, v108, v109
	v_cvt_pk_bf16_f32 v107, v110, v111
	global_store_dwordx4 v[112:113], v[104:107], off
	v_cvt_pk_bf16_f32 v91, v90, v91
	v_cvt_pk_bf16_f32 v90, v88, v89
	v_cvt_pk_bf16_f32 v88, v96, v97
	v_cvt_pk_bf16_f32 v89, v98, v99
	global_store_dwordx4 v[112:113], v[88:91], off offset:256
	s_nop 1
	v_or_b32_e32 v88, 32, v158
	v_mad_i64_i32 v[88:89], s[24:25], v88, s49, v[144:145]
	v_lshl_add_u64 v[96:97], v[88:89], 0, v[146:147]
	v_pk_add_f32 v[90:91], v[102:103], 0 op_sel_hi:[1,0]
	v_pk_add_f32 v[88:89], v[100:101], 0 op_sel_hi:[1,0]
	v_cvt_pk_bf16_f32 v88, v88, v89
	v_cvt_pk_bf16_f32 v89, v90, v91
	v_cvt_pk_bf16_f32 v90, v92, v93
	v_cvt_pk_bf16_f32 v91, v94, v95
	global_store_dwordx4 v[96:97], v[88:91], off
	v_cvt_pk_bf16_f32 v75, v74, v75
	v_cvt_pk_bf16_f32 v74, v72, v73
	v_cvt_pk_bf16_f32 v72, v80, v81
	v_cvt_pk_bf16_f32 v73, v82, v83
	global_store_dwordx4 v[96:97], v[72:75], off offset:256
	s_nop 1
	v_or_b32_e32 v72, 48, v158
	v_mad_i64_i32 v[72:73], s[24:25], v72, s49, v[144:145]
	v_lshl_add_u64 v[80:81], v[72:73], 0, v[146:147]
	v_pk_add_f32 v[74:75], v[86:87], 0 op_sel_hi:[1,0]
	v_pk_add_f32 v[72:73], v[84:85], 0 op_sel_hi:[1,0]
	v_cvt_pk_bf16_f32 v72, v72, v73
	v_cvt_pk_bf16_f32 v73, v74, v75
	v_cvt_pk_bf16_f32 v74, v76, v77
	v_cvt_pk_bf16_f32 v75, v78, v79
	global_store_dwordx4 v[80:81], v[72:75], off
	v_cvt_pk_bf16_f32 v67, v66, v67
	v_cvt_pk_bf16_f32 v66, v64, v65
	v_cvt_pk_bf16_f32 v64, v68, v69
	v_cvt_pk_bf16_f32 v65, v70, v71
	global_store_dwordx4 v[80:81], v[64:67], off offset:256
	s_nop 1
	v_add_u32_e32 v64, 0x80, v158
	v_mad_i64_i32 v[64:65], s[24:25], v64, s49, v[144:145]
	v_pk_add_f32 v[66:67], v[58:59], 0 op_sel_hi:[1,0]
	v_pk_add_f32 v[58:59], v[56:57], 0 op_sel_hi:[1,0]
	v_lshl_add_u64 v[64:65], v[64:65], 0, v[146:147]
	v_cvt_pk_bf16_f32 v56, v60, v61
	v_cvt_pk_bf16_f32 v57, v62, v63
	v_cvt_pk_bf16_f32 v58, v58, v59
	v_cvt_pk_bf16_f32 v59, v66, v67
	global_store_dwordx4 v[64:65], v[56:59], off
	v_cvt_pk_bf16_f32 v43, v42, v43
	v_cvt_pk_bf16_f32 v42, v40, v41
	v_cvt_pk_bf16_f32 v40, v48, v49
	v_cvt_pk_bf16_f32 v41, v50, v51
	global_store_dwordx4 v[64:65], v[40:43], off offset:256
	s_nop 1
	v_add_u32_e32 v40, 0x90, v158
	v_mad_i64_i32 v[40:41], s[24:25], v40, s49, v[144:145]
	v_lshl_add_u64 v[48:49], v[40:41], 0, v[146:147]
	v_pk_add_f32 v[42:43], v[54:55], 0 op_sel_hi:[1,0]
	v_pk_add_f32 v[40:41], v[52:53], 0 op_sel_hi:[1,0]
	v_cvt_pk_bf16_f32 v40, v40, v41
	v_cvt_pk_bf16_f32 v41, v42, v43
	v_cvt_pk_bf16_f32 v42, v44, v45
	v_cvt_pk_bf16_f32 v43, v46, v47
	global_store_dwordx4 v[48:49], v[40:43], off
	v_cvt_pk_bf16_f32 v27, v26, v27
	v_cvt_pk_bf16_f32 v26, v24, v25
	v_cvt_pk_bf16_f32 v24, v32, v33
	v_cvt_pk_bf16_f32 v25, v34, v35
	global_store_dwordx4 v[48:49], v[24:27], off offset:256
	s_nop 1
	v_add_u32_e32 v24, 0xa0, v158
	v_mad_i64_i32 v[24:25], s[24:25], v24, s49, v[144:145]
	v_lshl_add_u64 v[32:33], v[24:25], 0, v[146:147]
	v_pk_add_f32 v[26:27], v[38:39], 0 op_sel_hi:[1,0]
	v_pk_add_f32 v[24:25], v[36:37], 0 op_sel_hi:[1,0]
	v_cvt_pk_bf16_f32 v24, v24, v25
	v_cvt_pk_bf16_f32 v25, v26, v27
	v_cvt_pk_bf16_f32 v26, v28, v29
	v_cvt_pk_bf16_f32 v27, v30, v31
	global_store_dwordx4 v[32:33], v[24:27], off
	s_nop 0
	s_andn2_b64 vcc, exec, s[2:3]
	v_pk_add_f32 v[24:25], v[10:11], 0 op_sel_hi:[1,0]
	v_pk_add_f32 v[10:11], v[8:9], 0 op_sel_hi:[1,0]
	v_cvt_pk_bf16_f32 v8, v16, v17
	v_cvt_pk_bf16_f32 v9, v18, v19
	v_cvt_pk_bf16_f32 v10, v10, v11
	v_cvt_pk_bf16_f32 v11, v24, v25
	global_store_dwordx4 v[32:33], v[8:11], off offset:256
	s_mov_b64 s[2:3], -1
	s_nop 0
	v_add_u32_e32 v8, 0xb0, v158
	v_mad_i64_i32 v[8:9], s[24:25], v8, s49, v[144:145]
	v_lshl_add_u64 v[16:17], v[8:9], 0, v[146:147]
	v_pk_add_f32 v[10:11], v[22:23], 0 op_sel_hi:[1,0]
	v_pk_add_f32 v[8:9], v[20:21], 0 op_sel_hi:[1,0]
	s_nop 0
	v_cvt_pk_bf16_f32 v8, v8, v9
	v_cvt_pk_bf16_f32 v9, v10, v11
	v_cvt_pk_bf16_f32 v10, v12, v13
	v_cvt_pk_bf16_f32 v11, v14, v15
	global_store_dwordx4 v[16:17], v[8:11], off
	s_nop 1
	v_pk_add_f32 v[8:9], v[2:3], 0 op_sel_hi:[1,0]
	v_pk_add_f32 v[2:3], v[0:1], 0 op_sel_hi:[1,0]
	v_cvt_pk_bf16_f32 v0, v4, v5
	v_cvt_pk_bf16_f32 v1, v6, v7
	v_cvt_pk_bf16_f32 v2, v2, v3
	v_cvt_pk_bf16_f32 v3, v8, v9
	global_store_dwordx4 v[16:17], v[0:3], off offset:256
	s_cbranch_vccnz .LBB0_2286
	s_andn2_b64 vcc, exec, s[4:5]
	s_cbranch_vccnz .LBB0_2285
	s_barrier
	s_branch .LBB0_2285

.LBB0_2429:
	v_lshl_or_b32 v146, s24, 8, v150
	v_lshl_add_u32 v158, s22, 8, v148
	v_add_u32_e32 v154, 0xffffbc00, v158
	v_ashrrev_i32_e32 v147, 31, v146
	v_mov_b64_e32 v[144:145], s[58:59]
	v_mad_i64_i32 v[154:155], s[24:25], v154, s49, v[144:145]
	v_lshlrev_b64 v[146:147], 1, v[146:147]
	v_pk_add_f32 v[156:157], v[122:123], 0 op_sel_hi:[1,0]
	v_pk_add_f32 v[122:123], v[120:121], 0 op_sel_hi:[1,0]
	v_lshl_add_u64 v[154:155], v[154:155], 0, v[146:147]
	v_cvt_pk_bf16_f32 v120, v124, v125
	v_cvt_pk_bf16_f32 v121, v126, v127
	v_cvt_pk_bf16_f32 v122, v122, v123
	v_cvt_pk_bf16_f32 v123, v156, v157
	global_store_dwordx4 v[154:155], v[120:123], off
	v_cvt_pk_bf16_f32 v107, v106, v107
	v_cvt_pk_bf16_f32 v106, v104, v105
	v_cvt_pk_bf16_f32 v104, v112, v113
	v_cvt_pk_bf16_f32 v105, v114, v115
	global_store_dwordx4 v[154:155], v[104:107], off offset:256
	s_nop 1
	v_add_u32_e32 v104, 0xffffbc10, v158
	v_mad_i64_i32 v[104:105], s[24:25], v104, s49, v[144:145]
	v_lshl_add_u64 v[112:113], v[104:105], 0, v[146:147]
	v_pk_add_f32 v[106:107], v[118:119], 0 op_sel_hi:[1,0]
	v_pk_add_f32 v[104:105], v[116:117], 0 op_sel_hi:[1,0]
	v_cvt_pk_bf16_f32 v104, v104, v105
	v_cvt_pk_bf16_f32 v105, v106, v107
	v_cvt_pk_bf16_f32 v106, v108, v109
	v_cvt_pk_bf16_f32 v107, v110, v111
	global_store_dwordx4 v[112:113], v[104:107], off
	v_cvt_pk_bf16_f32 v91, v90, v91
	v_cvt_pk_bf16_f32 v90, v88, v89
	v_cvt_pk_bf16_f32 v88, v96, v97
	v_cvt_pk_bf16_f32 v89, v98, v99
	global_store_dwordx4 v[112:113], v[88:91], off offset:256
	s_nop 1
	v_add_u32_e32 v88, 0xffffbc20, v158
	v_mad_i64_i32 v[88:89], s[24:25], v88, s49, v[144:145]
	v_lshl_add_u64 v[96:97], v[88:89], 0, v[146:147]
	v_pk_add_f32 v[90:91], v[102:103], 0 op_sel_hi:[1,0]
	v_pk_add_f32 v[88:89], v[100:101], 0 op_sel_hi:[1,0]
	v_cvt_pk_bf16_f32 v88, v88, v89
	v_cvt_pk_bf16_f32 v89, v90, v91
	v_cvt_pk_bf16_f32 v90, v92, v93
	v_cvt_pk_bf16_f32 v91, v94, v95
	global_store_dwordx4 v[96:97], v[88:91], off
	v_cvt_pk_bf16_f32 v75, v74, v75
	v_cvt_pk_bf16_f32 v74, v72, v73
	v_cvt_pk_bf16_f32 v72, v80, v81
	v_cvt_pk_bf16_f32 v73, v82, v83
	global_store_dwordx4 v[96:97], v[72:75], off offset:256
	s_nop 1
	v_add_u32_e32 v72, 0xffffbc30, v158
	v_mad_i64_i32 v[72:73], s[24:25], v72, s49, v[144:145]
	v_lshl_add_u64 v[80:81], v[72:73], 0, v[146:147]
	v_pk_add_f32 v[74:75], v[86:87], 0 op_sel_hi:[1,0]
	v_pk_add_f32 v[72:73], v[84:85], 0 op_sel_hi:[1,0]
	v_cvt_pk_bf16_f32 v72, v72, v73
	v_cvt_pk_bf16_f32 v73, v74, v75
	v_cvt_pk_bf16_f32 v74, v76, v77
	v_cvt_pk_bf16_f32 v75, v78, v79
	global_store_dwordx4 v[80:81], v[72:75], off
	v_cvt_pk_bf16_f32 v67, v66, v67
	v_cvt_pk_bf16_f32 v66, v64, v65
	v_cvt_pk_bf16_f32 v64, v68, v69
	v_cvt_pk_bf16_f32 v65, v70, v71
	global_store_dwordx4 v[80:81], v[64:67], off offset:256
	s_nop 1
	v_add_u32_e32 v64, 0xffffbc80, v158
	v_mad_i64_i32 v[64:65], s[24:25], v64, s49, v[144:145]
	v_pk_add_f32 v[66:67], v[58:59], 0 op_sel_hi:[1,0]
	v_pk_add_f32 v[58:59], v[56:57], 0 op_sel_hi:[1,0]
	v_lshl_add_u64 v[64:65], v[64:65], 0, v[146:147]
	v_cvt_pk_bf16_f32 v56, v60, v61
	v_cvt_pk_bf16_f32 v57, v62, v63
	v_cvt_pk_bf16_f32 v58, v58, v59
	v_cvt_pk_bf16_f32 v59, v66, v67
	global_store_dwordx4 v[64:65], v[56:59], off
	v_cvt_pk_bf16_f32 v43, v42, v43
	v_cvt_pk_bf16_f32 v42, v40, v41
	v_cvt_pk_bf16_f32 v40, v48, v49
	v_cvt_pk_bf16_f32 v41, v50, v51
	global_store_dwordx4 v[64:65], v[40:43], off offset:256
	s_nop 1
	v_add_u32_e32 v40, 0xffffbc90, v158
	v_mad_i64_i32 v[40:41], s[24:25], v40, s49, v[144:145]
	v_lshl_add_u64 v[48:49], v[40:41], 0, v[146:147]
	v_pk_add_f32 v[42:43], v[54:55], 0 op_sel_hi:[1,0]
	v_pk_add_f32 v[40:41], v[52:53], 0 op_sel_hi:[1,0]
	v_cvt_pk_bf16_f32 v40, v40, v41
	v_cvt_pk_bf16_f32 v41, v42, v43
	v_cvt_pk_bf16_f32 v42, v44, v45
	v_cvt_pk_bf16_f32 v43, v46, v47
	global_store_dwordx4 v[48:49], v[40:43], off
	v_cvt_pk_bf16_f32 v27, v26, v27
	v_cvt_pk_bf16_f32 v26, v24, v25
	v_cvt_pk_bf16_f32 v24, v32, v33
	v_cvt_pk_bf16_f32 v25, v34, v35
	global_store_dwordx4 v[48:49], v[24:27], off offset:256
	s_nop 1
	v_add_u32_e32 v24, 0xffffbca0, v158
	v_mad_i64_i32 v[24:25], s[24:25], v24, s49, v[144:145]
	v_lshl_add_u64 v[32:33], v[24:25], 0, v[146:147]
	v_pk_add_f32 v[26:27], v[38:39], 0 op_sel_hi:[1,0]
	v_pk_add_f32 v[24:25], v[36:37], 0 op_sel_hi:[1,0]
	v_cvt_pk_bf16_f32 v24, v24, v25
	v_cvt_pk_bf16_f32 v25, v26, v27
	v_cvt_pk_bf16_f32 v26, v28, v29
	v_cvt_pk_bf16_f32 v27, v30, v31
	global_store_dwordx4 v[32:33], v[24:27], off
	s_nop 0
	s_andn2_b64 vcc, exec, s[2:3]
	v_pk_add_f32 v[24:25], v[10:11], 0 op_sel_hi:[1,0]
	v_pk_add_f32 v[10:11], v[8:9], 0 op_sel_hi:[1,0]
	v_cvt_pk_bf16_f32 v8, v16, v17
	v_cvt_pk_bf16_f32 v9, v18, v19
	v_cvt_pk_bf16_f32 v10, v10, v11
	v_cvt_pk_bf16_f32 v11, v24, v25
	global_store_dwordx4 v[32:33], v[8:11], off offset:256
	s_mov_b64 s[2:3], -1
	s_nop 0
	v_add_u32_e32 v8, 0xffffbcb0, v158
	v_mad_i64_i32 v[8:9], s[24:25], v8, s49, v[144:145]
	v_lshl_add_u64 v[16:17], v[8:9], 0, v[146:147]
	v_pk_add_f32 v[10:11], v[22:23], 0 op_sel_hi:[1,0]
	v_pk_add_f32 v[8:9], v[20:21], 0 op_sel_hi:[1,0]
	s_nop 0
	v_cvt_pk_bf16_f32 v8, v8, v9
	v_cvt_pk_bf16_f32 v9, v10, v11
	v_cvt_pk_bf16_f32 v10, v12, v13
	v_cvt_pk_bf16_f32 v11, v14, v15
	global_store_dwordx4 v[16:17], v[8:11], off
	s_nop 1
	v_pk_add_f32 v[8:9], v[2:3], 0 op_sel_hi:[1,0]
	v_pk_add_f32 v[2:3], v[0:1], 0 op_sel_hi:[1,0]
	v_cvt_pk_bf16_f32 v0, v4, v5
	v_cvt_pk_bf16_f32 v1, v6, v7
	v_cvt_pk_bf16_f32 v2, v2, v3
	v_cvt_pk_bf16_f32 v3, v8, v9
	global_store_dwordx4 v[16:17], v[0:3], off offset:256
	s_cbranch_vccnz .LBB0_2422
	s_andn2_b64 vcc, exec, s[4:5]
	s_cbranch_vccnz .LBB0_2421
	s_barrier
	s_branch .LBB0_2421
